# barrier: + acquire invalidate issued at arrival (overlaps the wait)
# speedup vs baseline: 1.0184x; 1.0184x over previous
.LBB0_461:
	s_andn2_saveexec_b64 s[4:5], s[4:5]
	s_cbranch_execz .LBB0_481
	s_mov_b64 s[4:5], exec
	v_mov_b32_e32 v8, v3
	buffer_inv sc1
	s_waitcnt lgkmcnt(0)
	s_waitcnt vmcnt(0)
	v_mbcnt_lo_u32_b32 v3, s4, 0
	v_mbcnt_hi_u32_b32 v3, s5, v3
	v_cmp_eq_u32_e32 vcc, 0, v3
	s_and_saveexec_b64 s[6:7], vcc
	s_cbranch_execz .LBB0_464
	s_bcnt1_i32_b64 s4, s[4:5]
	v_mov_b32_e32 v5, s4
	v_readlane_b32 s4, v253, 9
	v_readlane_b32 s5, v253, 10
	s_nop 4
	global_atomic_add v5, v4, v5, s[4:5] sc0

.LBB0_551:
	s_andn2_saveexec_b64 s[6:7], s[6:7]
	s_cbranch_execz .LBB0_571
	s_mov_b64 s[6:7], exec
	v_mov_b32_e32 v8, v3
	buffer_inv sc1
	s_waitcnt lgkmcnt(0)
	s_waitcnt vmcnt(0)
	v_mbcnt_lo_u32_b32 v3, s6, 0
	v_mbcnt_hi_u32_b32 v3, s7, v3
	v_cmp_eq_u32_e32 vcc, 0, v3
	s_and_saveexec_b64 s[8:9], vcc
	s_cbranch_execz .LBB0_554
	s_bcnt1_i32_b64 s6, s[6:7]
	v_mov_b32_e32 v5, s6
	v_readlane_b32 s6, v253, 9
	v_readlane_b32 s7, v253, 10
	s_nop 4
	global_atomic_add v5, v4, v5, s[6:7] sc0
